# selected loop waits for the K fragments before QK and for the V fragments only before PV
# speedup vs baseline: 1.0232x; 1.0040x over previous
; __device__ __forceinline__ f32x4v mfma16(bf16x8 a, bf16x8 b, f32x4v c) { return __builtin_amdgcn_mfma_f32_16x16x32_bf16(a, b, c, 0, 0, 0); }
; __device__ __forceinline__ void flash16_compute(bool domask, const bf16x8 (&kf)[4], const bf16x8 (&vf)[4], const bf16x8 (&q)[2], int x0, unsigned span, float& m, float& l, f32x4v (&O)[4]) {
;     f32x4v s0 = {0.f, 0.f, 0.f, 0.f}, s1 = {0.f, 0.f, 0.f, 0.f};
;     __builtin_amdgcn_s_setprio(1);
;     s0 = mfma16(kf[0], q[0], s0); s1 = mfma16(kf[2], q[0], s1);
;     s0 = mfma16(kf[1], q[1], s0); s1 = mfma16(kf[3], q[1], s1);
.Lsel_step_A:
	s_waitcnt lgkmcnt(0)
	v_readfirstlane_b32 s4, v54
	ds_read_b32 v54, v55
	v_add_u32_e32 v55, 4, v55
	s_and_b32 s6, s4, 0x7fff
	s_lshl_b32 s6, s6, 12
	v_lshl_add_u64 v[56:57], v[230:231], 0, s[6:7]
	v_lshl_add_u64 v[58:59], v[234:235], 0, s[6:7]
	global_load_dwordx4 v[62:65], v[56:57], off
	global_load_dwordx4 v[66:69], v[56:57], off offset:1024
	global_load_dwordx4 v[70:73], v[56:57], off offset:2048
	global_load_dwordx4 v[74:77], v[56:57], off offset:3072
	global_load_dwordx4 v[78:81], v[58:59], off
	global_load_dwordx4 v[82:85], v[58:59], off offset:1024
	global_load_dwordx4 v[86:89], v[58:59], off offset:2048
	global_load_dwordx4 v[90:93], v[58:59], off offset:3072
	s_bfe_u32 s12, s16, 0x40010
	s_bfe_u32 s13, s16, 0x40014
	s_waitcnt vmcnt(28)
	s_cmp_eq_u32 s12, 0
	s_cbranch_scc1 .Lsel_skip_Aa
	v_and_b32_e32 v14, s12, v225
	v_cmp_eq_u32_e32 vcc, 0, v14
	s_bitcmp0_b32 s16, 15
	s_cbranch_scc1 .Lsel_slow_Aa
	v_cndmask_b32_e32 v10, v240, v249, vcc
	v_mov_b32_e32 v11, v10
	v_mov_b32_e32 v12, v10
	v_mov_b32_e32 v13, v10
	s_nop 1
	v_mfma_f32_16x16x32_bf16 v[2:5], v[114:117], v[102:105], v[10:13]
	v_mfma_f32_16x16x32_bf16 v[6:9], v[122:125], v[102:105], v[10:13]

; __device__ __forceinline__ float ex2(float x) { return __builtin_amdgcn_exp2f(x); }
; __device__ __forceinline__ bf16x8 pack_p(const float* p) { u32x4 w; w.x = cvt_pk_bf16(p[0], p[1]); w.y = cvt_pk_bf16(p[2], p[3]); w.z = cvt_pk_bf16(p[4], p[5]); w.w = cvt_pk_bf16(p[6], p[7]); return __builtin_bit_cast(bf16x8, w); }
; __device__ __forceinline__ f32x4v mfma16(bf16x8 a, bf16x8 b, f32x4v c) { return __builtin_amdgcn_mfma_f32_16x16x32_bf16(a, b, c, 0, 0, 0); }
; __device__ __forceinline__ void flash16_compute(bool domask, const bf16x8 (&kf)[4], const bf16x8 (&vf)[4], const bf16x8 (&q)[2], int x0, unsigned span, float& m, float& l, f32x4v (&O)[4]) {
;     ...
;     const float msub = (m < -1e29f) ? 0.f : m;
;     float p[8], ps = 0.f;
; #pragma unroll
;     for (int j = 0; j < 8; ++j) { p[j] = ex2(sc[j] - msub); ps += p[j]; }
;     l += ps;
;     const bf16x8 pb = pack_p(p);
;     __builtin_amdgcn_s_setprio(1);
; #pragma unroll
;     for (int dt = 0; dt < 4; ++dt) O[dt] = mfma16(vf[dt], pb, O[dt]);
;     __builtin_amdgcn_s_setprio(0);
.Lsel_noupd_Aa:
	v_exp_f32_e32 v2, v2
	v_exp_f32_e32 v3, v3
	v_exp_f32_e32 v4, v4
	v_exp_f32_e32 v5, v5
	v_add_f32_e32 v14, v2, v3
	v_exp_f32_e32 v6, v6
	v_cvt_pk_bf16_f32 v50, v2, v3
	v_add_f32_e32 v14, v14, v4
	v_exp_f32_e32 v7, v7
	v_add_f32_e32 v14, v14, v5
	v_exp_f32_e32 v8, v8
	v_cvt_pk_bf16_f32 v51, v4, v5
	v_add_f32_e32 v14, v14, v6
	v_exp_f32_e32 v9, v9
	v_add_f32_e32 v14, v14, v7
	v_cvt_pk_bf16_f32 v52, v6, v7
	v_add_f32_e32 v14, v14, v8
	v_cvt_pk_bf16_f32 v53, v8, v9
	v_add_f32_e32 v14, v14, v9
	v_add_f32_e32 v238, v238, v14
	s_waitcnt vmcnt(24)
	v_mfma_f32_16x16x32_bf16 v[34:37], v[130:133], v[50:53], v[34:37]
	v_mfma_f32_16x16x32_bf16 v[38:41], v[134:137], v[50:53], v[38:41]
	v_mfma_f32_16x16x32_bf16 v[42:45], v[138:141], v[50:53], v[42:45]
	v_mfma_f32_16x16x32_bf16 v[46:49], v[142:145], v[50:53], v[46:49]

; __device__ __forceinline__ float ex2(float x) { return __builtin_amdgcn_exp2f(x); }
; __device__ __forceinline__ bf16x8 pack_p(const float* p) { u32x4 w; w.x = cvt_pk_bf16(p[0], p[1]); w.y = cvt_pk_bf16(p[2], p[3]); w.z = cvt_pk_bf16(p[4], p[5]); w.w = cvt_pk_bf16(p[6], p[7]); return __builtin_bit_cast(bf16x8, w); }
; __device__ __forceinline__ f32x4v mfma16(bf16x8 a, bf16x8 b, f32x4v c) { return __builtin_amdgcn_mfma_f32_16x16x32_bf16(a, b, c, 0, 0, 0); }
; __device__ __forceinline__ void flash16_compute(bool domask, const bf16x8 (&kf)[4], const bf16x8 (&vf)[4], const bf16x8 (&q)[2], int x0, unsigned span, float& m, float& l, f32x4v (&O)[4]) {
;     ...
;     const float msub = (m < -1e29f) ? 0.f : m;
;     float p[8], ps = 0.f;
; #pragma unroll
;     for (int j = 0; j < 8; ++j) { p[j] = ex2(sc[j] - msub); ps += p[j]; }
;     l += ps;
;     const bf16x8 pb = pack_p(p);
;     __builtin_amdgcn_s_setprio(1);
; #pragma unroll
;     for (int dt = 0; dt < 4; ++dt) O[dt] = mfma16(vf[dt], pb, O[dt]);
;     __builtin_amdgcn_s_setprio(0);
.Lsel_noupd_Ab:
	v_exp_f32_e32 v2, v2
	v_exp_f32_e32 v3, v3
	v_exp_f32_e32 v4, v4
	v_exp_f32_e32 v5, v5
	v_add_f32_e32 v14, v2, v3
	v_exp_f32_e32 v6, v6
	v_cvt_pk_bf16_f32 v50, v2, v3
	v_add_f32_e32 v14, v14, v4
	v_exp_f32_e32 v7, v7
	v_add_f32_e32 v14, v14, v5
	v_exp_f32_e32 v8, v8
	v_cvt_pk_bf16_f32 v51, v4, v5
	v_add_f32_e32 v14, v14, v6
	v_exp_f32_e32 v9, v9
	v_add_f32_e32 v14, v14, v7
	v_cvt_pk_bf16_f32 v52, v6, v7
	v_add_f32_e32 v14, v14, v8
	v_cvt_pk_bf16_f32 v53, v8, v9
	v_add_f32_e32 v14, v14, v9
	v_add_f32_e32 v239, v239, v14
	s_waitcnt vmcnt(24)
	v_mfma_f32_16x16x32_bf16 v[18:21], v[130:133], v[50:53], v[18:21]
	v_mfma_f32_16x16x32_bf16 v[22:25], v[134:137], v[50:53], v[22:25]
	v_mfma_f32_16x16x32_bf16 v[26:29], v[138:141], v[50:53], v[26:29]
	v_mfma_f32_16x16x32_bf16 v[30:33], v[142:145], v[50:53], v[30:33]

; __device__ __forceinline__ f32x4v mfma16(bf16x8 a, bf16x8 b, f32x4v c) { return __builtin_amdgcn_mfma_f32_16x16x32_bf16(a, b, c, 0, 0, 0); }
; __device__ __forceinline__ void flash16_compute(bool domask, const bf16x8 (&kf)[4], const bf16x8 (&vf)[4], const bf16x8 (&q)[2], int x0, unsigned span, float& m, float& l, f32x4v (&O)[4]) {
;     f32x4v s0 = {0.f, 0.f, 0.f, 0.f}, s1 = {0.f, 0.f, 0.f, 0.f};
;     __builtin_amdgcn_s_setprio(1);
;     s0 = mfma16(kf[0], q[0], s0); s1 = mfma16(kf[2], q[0], s1);
;     s0 = mfma16(kf[1], q[1], s0); s1 = mfma16(kf[3], q[1], s1);
.Lsel_step_B:
	s_waitcnt lgkmcnt(0)
	v_readfirstlane_b32 s16, v54
	ds_read_b32 v54, v55
	v_add_u32_e32 v55, 4, v55
	s_and_b32 s6, s16, 0x7fff
	s_lshl_b32 s6, s6, 12
	v_lshl_add_u64 v[56:57], v[230:231], 0, s[6:7]
	v_lshl_add_u64 v[58:59], v[234:235], 0, s[6:7]
	global_load_dwordx4 v[114:117], v[56:57], off
	global_load_dwordx4 v[118:121], v[56:57], off offset:1024
	global_load_dwordx4 v[122:125], v[56:57], off offset:2048
	global_load_dwordx4 v[126:129], v[56:57], off offset:3072
	global_load_dwordx4 v[130:133], v[58:59], off
	global_load_dwordx4 v[134:137], v[58:59], off offset:1024
	global_load_dwordx4 v[138:141], v[58:59], off offset:2048
	global_load_dwordx4 v[142:145], v[58:59], off offset:3072
	s_bfe_u32 s12, s17, 0x40010
	s_bfe_u32 s13, s17, 0x40014
	s_waitcnt vmcnt(28)
	s_cmp_eq_u32 s12, 0
	s_cbranch_scc1 .Lsel_skip_Ba
	v_and_b32_e32 v14, s12, v225
	v_cmp_eq_u32_e32 vcc, 0, v14
	s_bitcmp0_b32 s17, 15
	s_cbranch_scc1 .Lsel_slow_Ba
	v_cndmask_b32_e32 v10, v240, v249, vcc
	v_mov_b32_e32 v11, v10
	v_mov_b32_e32 v12, v10
	v_mov_b32_e32 v13, v10
	s_nop 1
	v_mfma_f32_16x16x32_bf16 v[2:5], v[146:149], v[102:105], v[10:13]
	v_mfma_f32_16x16x32_bf16 v[6:9], v[154:157], v[102:105], v[10:13]

; __device__ __forceinline__ float ex2(float x) { return __builtin_amdgcn_exp2f(x); }
; __device__ __forceinline__ bf16x8 pack_p(const float* p) { u32x4 w; w.x = cvt_pk_bf16(p[0], p[1]); w.y = cvt_pk_bf16(p[2], p[3]); w.z = cvt_pk_bf16(p[4], p[5]); w.w = cvt_pk_bf16(p[6], p[7]); return __builtin_bit_cast(bf16x8, w); }
; __device__ __forceinline__ f32x4v mfma16(bf16x8 a, bf16x8 b, f32x4v c) { return __builtin_amdgcn_mfma_f32_16x16x32_bf16(a, b, c, 0, 0, 0); }
; __device__ __forceinline__ void flash16_compute(bool domask, const bf16x8 (&kf)[4], const bf16x8 (&vf)[4], const bf16x8 (&q)[2], int x0, unsigned span, float& m, float& l, f32x4v (&O)[4]) {
;     ...
;     const float msub = (m < -1e29f) ? 0.f : m;
;     float p[8], ps = 0.f;
; #pragma unroll
;     for (int j = 0; j < 8; ++j) { p[j] = ex2(sc[j] - msub); ps += p[j]; }
;     l += ps;
;     const bf16x8 pb = pack_p(p);
;     __builtin_amdgcn_s_setprio(1);
; #pragma unroll
;     for (int dt = 0; dt < 4; ++dt) O[dt] = mfma16(vf[dt], pb, O[dt]);
;     __builtin_amdgcn_s_setprio(0);
.Lsel_noupd_Ba:
	v_exp_f32_e32 v2, v2
	v_exp_f32_e32 v3, v3
	v_exp_f32_e32 v4, v4
	v_exp_f32_e32 v5, v5
	v_add_f32_e32 v14, v2, v3
	v_exp_f32_e32 v6, v6
	v_cvt_pk_bf16_f32 v50, v2, v3
	v_add_f32_e32 v14, v14, v4
	v_exp_f32_e32 v7, v7
	v_add_f32_e32 v14, v14, v5
	v_exp_f32_e32 v8, v8
	v_cvt_pk_bf16_f32 v51, v4, v5
	v_add_f32_e32 v14, v14, v6
	v_exp_f32_e32 v9, v9
	v_add_f32_e32 v14, v14, v7
	v_cvt_pk_bf16_f32 v52, v6, v7
	v_add_f32_e32 v14, v14, v8
	v_cvt_pk_bf16_f32 v53, v8, v9
	v_add_f32_e32 v14, v14, v9
	v_add_f32_e32 v238, v238, v14
	s_waitcnt vmcnt(24)
	v_mfma_f32_16x16x32_bf16 v[34:37], v[162:165], v[50:53], v[34:37]
	v_mfma_f32_16x16x32_bf16 v[38:41], v[166:169], v[50:53], v[38:41]
	v_mfma_f32_16x16x32_bf16 v[42:45], v[170:173], v[50:53], v[42:45]
	v_mfma_f32_16x16x32_bf16 v[46:49], v[174:177], v[50:53], v[46:49]

; __device__ __forceinline__ float ex2(float x) { return __builtin_amdgcn_exp2f(x); }
; __device__ __forceinline__ bf16x8 pack_p(const float* p) { u32x4 w; w.x = cvt_pk_bf16(p[0], p[1]); w.y = cvt_pk_bf16(p[2], p[3]); w.z = cvt_pk_bf16(p[4], p[5]); w.w = cvt_pk_bf16(p[6], p[7]); return __builtin_bit_cast(bf16x8, w); }
; __device__ __forceinline__ f32x4v mfma16(bf16x8 a, bf16x8 b, f32x4v c) { return __builtin_amdgcn_mfma_f32_16x16x32_bf16(a, b, c, 0, 0, 0); }
; __device__ __forceinline__ void flash16_compute(bool domask, const bf16x8 (&kf)[4], const bf16x8 (&vf)[4], const bf16x8 (&q)[2], int x0, unsigned span, float& m, float& l, f32x4v (&O)[4]) {
;     ...
;     const float msub = (m < -1e29f) ? 0.f : m;
;     float p[8], ps = 0.f;
; #pragma unroll
;     for (int j = 0; j < 8; ++j) { p[j] = ex2(sc[j] - msub); ps += p[j]; }
;     l += ps;
;     const bf16x8 pb = pack_p(p);
;     __builtin_amdgcn_s_setprio(1);
; #pragma unroll
;     for (int dt = 0; dt < 4; ++dt) O[dt] = mfma16(vf[dt], pb, O[dt]);
;     __builtin_amdgcn_s_setprio(0);
.Lsel_noupd_Bb:
	v_exp_f32_e32 v2, v2
	v_exp_f32_e32 v3, v3
	v_exp_f32_e32 v4, v4
	v_exp_f32_e32 v5, v5
	v_add_f32_e32 v14, v2, v3
	v_exp_f32_e32 v6, v6
	v_cvt_pk_bf16_f32 v50, v2, v3
	v_add_f32_e32 v14, v14, v4
	v_exp_f32_e32 v7, v7
	v_add_f32_e32 v14, v14, v5
	v_exp_f32_e32 v8, v8
	v_cvt_pk_bf16_f32 v51, v4, v5
	v_add_f32_e32 v14, v14, v6
	v_exp_f32_e32 v9, v9
	v_add_f32_e32 v14, v14, v7
	v_cvt_pk_bf16_f32 v52, v6, v7
	v_add_f32_e32 v14, v14, v8
	v_cvt_pk_bf16_f32 v53, v8, v9
	v_add_f32_e32 v14, v14, v9
	v_add_f32_e32 v239, v239, v14
	s_waitcnt vmcnt(24)
	v_mfma_f32_16x16x32_bf16 v[18:21], v[162:165], v[50:53], v[18:21]
	v_mfma_f32_16x16x32_bf16 v[22:25], v[166:169], v[50:53], v[22:25]
	v_mfma_f32_16x16x32_bf16 v[26:29], v[170:173], v[50:53], v[26:29]
	v_mfma_f32_16x16x32_bf16 v[30:33], v[174:177], v[50:53], v[30:33]

; __device__ __forceinline__ f32x4v mfma16(bf16x8 a, bf16x8 b, f32x4v c) { return __builtin_amdgcn_mfma_f32_16x16x32_bf16(a, b, c, 0, 0, 0); }
; __device__ __forceinline__ void flash16_compute(bool domask, const bf16x8 (&kf)[4], const bf16x8 (&vf)[4], const bf16x8 (&q)[2], int x0, unsigned span, float& m, float& l, f32x4v (&O)[4]) {
;     f32x4v s0 = {0.f, 0.f, 0.f, 0.f}, s1 = {0.f, 0.f, 0.f, 0.f};
;     __builtin_amdgcn_s_setprio(1);
;     s0 = mfma16(kf[0], q[0], s0); s1 = mfma16(kf[2], q[0], s1);
;     s0 = mfma16(kf[1], q[1], s0); s1 = mfma16(kf[3], q[1], s1);
.Lsel_step_C:
	s_waitcnt lgkmcnt(0)
	v_readfirstlane_b32 s17, v54
	ds_read_b32 v54, v55
	v_add_u32_e32 v55, 4, v55
	s_and_b32 s6, s17, 0x7fff
	s_lshl_b32 s6, s6, 12
	v_lshl_add_u64 v[56:57], v[230:231], 0, s[6:7]
	v_lshl_add_u64 v[58:59], v[234:235], 0, s[6:7]
	global_load_dwordx4 v[146:149], v[56:57], off
	global_load_dwordx4 v[150:153], v[56:57], off offset:1024
	global_load_dwordx4 v[154:157], v[56:57], off offset:2048
	global_load_dwordx4 v[158:161], v[56:57], off offset:3072
	global_load_dwordx4 v[162:165], v[58:59], off
	global_load_dwordx4 v[166:169], v[58:59], off offset:1024
	global_load_dwordx4 v[170:173], v[58:59], off offset:2048
	global_load_dwordx4 v[174:177], v[58:59], off offset:3072
	s_bfe_u32 s12, s19, 0x40010
	s_bfe_u32 s13, s19, 0x40014
	s_waitcnt vmcnt(28)
	s_cmp_eq_u32 s12, 0
	s_cbranch_scc1 .Lsel_skip_Ca
	v_and_b32_e32 v14, s12, v225
	v_cmp_eq_u32_e32 vcc, 0, v14
	s_bitcmp0_b32 s19, 15
	s_cbranch_scc1 .Lsel_slow_Ca
	v_cndmask_b32_e32 v10, v240, v249, vcc
	v_mov_b32_e32 v11, v10
	v_mov_b32_e32 v12, v10
	v_mov_b32_e32 v13, v10
	s_nop 1
	v_mfma_f32_16x16x32_bf16 v[2:5], v[178:181], v[102:105], v[10:13]
	v_mfma_f32_16x16x32_bf16 v[6:9], v[186:189], v[102:105], v[10:13]

; __device__ __forceinline__ float ex2(float x) { return __builtin_amdgcn_exp2f(x); }
; __device__ __forceinline__ bf16x8 pack_p(const float* p) { u32x4 w; w.x = cvt_pk_bf16(p[0], p[1]); w.y = cvt_pk_bf16(p[2], p[3]); w.z = cvt_pk_bf16(p[4], p[5]); w.w = cvt_pk_bf16(p[6], p[7]); return __builtin_bit_cast(bf16x8, w); }
; __device__ __forceinline__ f32x4v mfma16(bf16x8 a, bf16x8 b, f32x4v c) { return __builtin_amdgcn_mfma_f32_16x16x32_bf16(a, b, c, 0, 0, 0); }
; __device__ __forceinline__ void flash16_compute(bool domask, const bf16x8 (&kf)[4], const bf16x8 (&vf)[4], const bf16x8 (&q)[2], int x0, unsigned span, float& m, float& l, f32x4v (&O)[4]) {
;     ...
;     const float msub = (m < -1e29f) ? 0.f : m;
;     float p[8], ps = 0.f;
; #pragma unroll
;     for (int j = 0; j < 8; ++j) { p[j] = ex2(sc[j] - msub); ps += p[j]; }
;     l += ps;
;     const bf16x8 pb = pack_p(p);
;     __builtin_amdgcn_s_setprio(1);
; #pragma unroll
;     for (int dt = 0; dt < 4; ++dt) O[dt] = mfma16(vf[dt], pb, O[dt]);
;     __builtin_amdgcn_s_setprio(0);
.Lsel_noupd_Ca:
	v_exp_f32_e32 v2, v2
	v_exp_f32_e32 v3, v3
	v_exp_f32_e32 v4, v4
	v_exp_f32_e32 v5, v5
	v_add_f32_e32 v14, v2, v3
	v_exp_f32_e32 v6, v6
	v_cvt_pk_bf16_f32 v50, v2, v3
	v_add_f32_e32 v14, v14, v4
	v_exp_f32_e32 v7, v7
	v_add_f32_e32 v14, v14, v5
	v_exp_f32_e32 v8, v8
	v_cvt_pk_bf16_f32 v51, v4, v5
	v_add_f32_e32 v14, v14, v6
	v_exp_f32_e32 v9, v9
	v_add_f32_e32 v14, v14, v7
	v_cvt_pk_bf16_f32 v52, v6, v7
	v_add_f32_e32 v14, v14, v8
	v_cvt_pk_bf16_f32 v53, v8, v9
	v_add_f32_e32 v14, v14, v9
	v_add_f32_e32 v238, v238, v14
	s_waitcnt vmcnt(24)
	v_mfma_f32_16x16x32_bf16 v[34:37], v[194:197], v[50:53], v[34:37]
	v_mfma_f32_16x16x32_bf16 v[38:41], v[198:201], v[50:53], v[38:41]
	v_mfma_f32_16x16x32_bf16 v[42:45], v[202:205], v[50:53], v[42:45]
	v_mfma_f32_16x16x32_bf16 v[46:49], v[206:209], v[50:53], v[46:49]

; __device__ __forceinline__ float ex2(float x) { return __builtin_amdgcn_exp2f(x); }
; __device__ __forceinline__ bf16x8 pack_p(const float* p) { u32x4 w; w.x = cvt_pk_bf16(p[0], p[1]); w.y = cvt_pk_bf16(p[2], p[3]); w.z = cvt_pk_bf16(p[4], p[5]); w.w = cvt_pk_bf16(p[6], p[7]); return __builtin_bit_cast(bf16x8, w); }
; __device__ __forceinline__ f32x4v mfma16(bf16x8 a, bf16x8 b, f32x4v c) { return __builtin_amdgcn_mfma_f32_16x16x32_bf16(a, b, c, 0, 0, 0); }
; __device__ __forceinline__ void flash16_compute(bool domask, const bf16x8 (&kf)[4], const bf16x8 (&vf)[4], const bf16x8 (&q)[2], int x0, unsigned span, float& m, float& l, f32x4v (&O)[4]) {
;     ...
;     const float msub = (m < -1e29f) ? 0.f : m;
;     float p[8], ps = 0.f;
; #pragma unroll
;     for (int j = 0; j < 8; ++j) { p[j] = ex2(sc[j] - msub); ps += p[j]; }
;     l += ps;
;     const bf16x8 pb = pack_p(p);
;     __builtin_amdgcn_s_setprio(1);
; #pragma unroll
;     for (int dt = 0; dt < 4; ++dt) O[dt] = mfma16(vf[dt], pb, O[dt]);
;     __builtin_amdgcn_s_setprio(0);
.Lsel_noupd_Cb:
	v_exp_f32_e32 v2, v2
	v_exp_f32_e32 v3, v3
	v_exp_f32_e32 v4, v4
	v_exp_f32_e32 v5, v5
	v_add_f32_e32 v14, v2, v3
	v_exp_f32_e32 v6, v6
	v_cvt_pk_bf16_f32 v50, v2, v3
	v_add_f32_e32 v14, v14, v4
	v_exp_f32_e32 v7, v7
	v_add_f32_e32 v14, v14, v5
	v_exp_f32_e32 v8, v8
	v_cvt_pk_bf16_f32 v51, v4, v5
	v_add_f32_e32 v14, v14, v6
	v_exp_f32_e32 v9, v9
	v_add_f32_e32 v14, v14, v7
	v_cvt_pk_bf16_f32 v52, v6, v7
	v_add_f32_e32 v14, v14, v8
	v_cvt_pk_bf16_f32 v53, v8, v9
	v_add_f32_e32 v14, v14, v9
	v_add_f32_e32 v239, v239, v14
	s_waitcnt vmcnt(24)
	v_mfma_f32_16x16x32_bf16 v[18:21], v[194:197], v[50:53], v[18:21]
	v_mfma_f32_16x16x32_bf16 v[22:25], v[198:201], v[50:53], v[22:25]
	v_mfma_f32_16x16x32_bf16 v[26:29], v[202:205], v[50:53], v[26:29]
	v_mfma_f32_16x16x32_bf16 v[30:33], v[206:209], v[50:53], v[30:33]

; __device__ __forceinline__ f32x4v mfma16(bf16x8 a, bf16x8 b, f32x4v c) { return __builtin_amdgcn_mfma_f32_16x16x32_bf16(a, b, c, 0, 0, 0); }
; __device__ __forceinline__ void flash16_compute(bool domask, const bf16x8 (&kf)[4], const bf16x8 (&vf)[4], const bf16x8 (&q)[2], int x0, unsigned span, float& m, float& l, f32x4v (&O)[4]) {
;     f32x4v s0 = {0.f, 0.f, 0.f, 0.f}, s1 = {0.f, 0.f, 0.f, 0.f};
;     __builtin_amdgcn_s_setprio(1);
;     s0 = mfma16(kf[0], q[0], s0); s1 = mfma16(kf[2], q[0], s1);
;     s0 = mfma16(kf[1], q[1], s0); s1 = mfma16(kf[3], q[1], s1);
.Lsel_step_D:
	s_waitcnt lgkmcnt(0)
	v_readfirstlane_b32 s19, v54
	ds_read_b32 v54, v55
	v_add_u32_e32 v55, 4, v55
	s_and_b32 s6, s19, 0x7fff
	s_lshl_b32 s6, s6, 12
	v_lshl_add_u64 v[56:57], v[230:231], 0, s[6:7]
	v_lshl_add_u64 v[58:59], v[234:235], 0, s[6:7]
	global_load_dwordx4 v[178:181], v[56:57], off
	global_load_dwordx4 v[182:185], v[56:57], off offset:1024
	global_load_dwordx4 v[186:189], v[56:57], off offset:2048
	global_load_dwordx4 v[190:193], v[56:57], off offset:3072
	global_load_dwordx4 v[194:197], v[58:59], off
	global_load_dwordx4 v[198:201], v[58:59], off offset:1024
	global_load_dwordx4 v[202:205], v[58:59], off offset:2048
	global_load_dwordx4 v[206:209], v[58:59], off offset:3072
	s_bfe_u32 s12, s4, 0x40010
	s_bfe_u32 s13, s4, 0x40014
	s_waitcnt vmcnt(28)
	s_cmp_eq_u32 s12, 0
	s_cbranch_scc1 .Lsel_skip_Da
	v_and_b32_e32 v14, s12, v225
	v_cmp_eq_u32_e32 vcc, 0, v14
	s_bitcmp0_b32 s4, 15
	s_cbranch_scc1 .Lsel_slow_Da
	v_cndmask_b32_e32 v10, v240, v249, vcc
	v_mov_b32_e32 v11, v10
	v_mov_b32_e32 v12, v10
	v_mov_b32_e32 v13, v10
	s_nop 1
	v_mfma_f32_16x16x32_bf16 v[2:5], v[62:65], v[102:105], v[10:13]
	v_mfma_f32_16x16x32_bf16 v[6:9], v[70:73], v[102:105], v[10:13]

; __device__ __forceinline__ float ex2(float x) { return __builtin_amdgcn_exp2f(x); }
; __device__ __forceinline__ bf16x8 pack_p(const float* p) { u32x4 w; w.x = cvt_pk_bf16(p[0], p[1]); w.y = cvt_pk_bf16(p[2], p[3]); w.z = cvt_pk_bf16(p[4], p[5]); w.w = cvt_pk_bf16(p[6], p[7]); return __builtin_bit_cast(bf16x8, w); }
; __device__ __forceinline__ f32x4v mfma16(bf16x8 a, bf16x8 b, f32x4v c) { return __builtin_amdgcn_mfma_f32_16x16x32_bf16(a, b, c, 0, 0, 0); }
; __device__ __forceinline__ void flash16_compute(bool domask, const bf16x8 (&kf)[4], const bf16x8 (&vf)[4], const bf16x8 (&q)[2], int x0, unsigned span, float& m, float& l, f32x4v (&O)[4]) {
;     ...
;     const float msub = (m < -1e29f) ? 0.f : m;
;     float p[8], ps = 0.f;
; #pragma unroll
;     for (int j = 0; j < 8; ++j) { p[j] = ex2(sc[j] - msub); ps += p[j]; }
;     l += ps;
;     const bf16x8 pb = pack_p(p);
;     __builtin_amdgcn_s_setprio(1);
; #pragma unroll
;     for (int dt = 0; dt < 4; ++dt) O[dt] = mfma16(vf[dt], pb, O[dt]);
;     __builtin_amdgcn_s_setprio(0);
.Lsel_noupd_Da:
	v_exp_f32_e32 v2, v2
	v_exp_f32_e32 v3, v3
	v_exp_f32_e32 v4, v4
	v_exp_f32_e32 v5, v5
	v_add_f32_e32 v14, v2, v3
	v_exp_f32_e32 v6, v6
	v_cvt_pk_bf16_f32 v50, v2, v3
	v_add_f32_e32 v14, v14, v4
	v_exp_f32_e32 v7, v7
	v_add_f32_e32 v14, v14, v5
	v_exp_f32_e32 v8, v8
	v_cvt_pk_bf16_f32 v51, v4, v5
	v_add_f32_e32 v14, v14, v6
	v_exp_f32_e32 v9, v9
	v_add_f32_e32 v14, v14, v7
	v_cvt_pk_bf16_f32 v52, v6, v7
	v_add_f32_e32 v14, v14, v8
	v_cvt_pk_bf16_f32 v53, v8, v9
	v_add_f32_e32 v14, v14, v9
	v_add_f32_e32 v238, v238, v14
	s_waitcnt vmcnt(24)
	v_mfma_f32_16x16x32_bf16 v[34:37], v[78:81], v[50:53], v[34:37]
	v_mfma_f32_16x16x32_bf16 v[38:41], v[82:85], v[50:53], v[38:41]
	v_mfma_f32_16x16x32_bf16 v[42:45], v[86:89], v[50:53], v[42:45]
	v_mfma_f32_16x16x32_bf16 v[46:49], v[90:93], v[50:53], v[46:49]

; __device__ __forceinline__ float ex2(float x) { return __builtin_amdgcn_exp2f(x); }
; __device__ __forceinline__ bf16x8 pack_p(const float* p) { u32x4 w; w.x = cvt_pk_bf16(p[0], p[1]); w.y = cvt_pk_bf16(p[2], p[3]); w.z = cvt_pk_bf16(p[4], p[5]); w.w = cvt_pk_bf16(p[6], p[7]); return __builtin_bit_cast(bf16x8, w); }
; __device__ __forceinline__ f32x4v mfma16(bf16x8 a, bf16x8 b, f32x4v c) { return __builtin_amdgcn_mfma_f32_16x16x32_bf16(a, b, c, 0, 0, 0); }
; __device__ __forceinline__ void flash16_compute(bool domask, const bf16x8 (&kf)[4], const bf16x8 (&vf)[4], const bf16x8 (&q)[2], int x0, unsigned span, float& m, float& l, f32x4v (&O)[4]) {
;     ...
;     const float msub = (m < -1e29f) ? 0.f : m;
;     float p[8], ps = 0.f;
; #pragma unroll
;     for (int j = 0; j < 8; ++j) { p[j] = ex2(sc[j] - msub); ps += p[j]; }
;     l += ps;
;     const bf16x8 pb = pack_p(p);
;     __builtin_amdgcn_s_setprio(1);
; #pragma unroll
;     for (int dt = 0; dt < 4; ++dt) O[dt] = mfma16(vf[dt], pb, O[dt]);
;     __builtin_amdgcn_s_setprio(0);
.Lsel_noupd_Db:
	v_exp_f32_e32 v2, v2
	v_exp_f32_e32 v3, v3
	v_exp_f32_e32 v4, v4
	v_exp_f32_e32 v5, v5
	v_add_f32_e32 v14, v2, v3
	v_exp_f32_e32 v6, v6
	v_cvt_pk_bf16_f32 v50, v2, v3
	v_add_f32_e32 v14, v14, v4
	v_exp_f32_e32 v7, v7
	v_add_f32_e32 v14, v14, v5
	v_exp_f32_e32 v8, v8
	v_cvt_pk_bf16_f32 v51, v4, v5
	v_add_f32_e32 v14, v14, v6
	v_exp_f32_e32 v9, v9
	v_add_f32_e32 v14, v14, v7
	v_cvt_pk_bf16_f32 v52, v6, v7
	v_add_f32_e32 v14, v14, v8
	v_cvt_pk_bf16_f32 v53, v8, v9
	v_add_f32_e32 v14, v14, v9
	v_add_f32_e32 v239, v239, v14
	s_waitcnt vmcnt(24)
	v_mfma_f32_16x16x32_bf16 v[18:21], v[78:81], v[50:53], v[18:21]
	v_mfma_f32_16x16x32_bf16 v[22:25], v[82:85], v[50:53], v[22:25]
	v_mfma_f32_16x16x32_bf16 v[26:29], v[86:89], v[50:53], v[26:29]
	v_mfma_f32_16x16x32_bf16 v[30:33], v[90:93], v[50:53], v[30:33]
